# v47 plus 8x8 per-XCD tile layout for the N=1024 GEMMs: each XCD takes 8 m-tiles x all 8 n-tiles per round (A crosses the fabric once, smaller per-k-step L2 fill)
# baseline (speedup 1.0000x reference)
; DI int otid() { int t = threadIdx.x; asm volatile("" : "+v"(t)); return t; }
; template <bool MERGE>
; DI void gemm_phase(const GemmDesc& d, const Params& P, char* lds) {
;   const int tid = otid(), lane = tid & 63, wid = tid >> 6, r = lane & 31, h = lane >> 5;
;   const int wm = wid >> 1, wn = wid & 1;
;   char* ws = ows(P);
;   const float* rope = reinterpret_cast<const float*>(ws + O_ROPE);
;   const int ntl = d.mtiles * d.ntiles;
;   for (int t = blockIdx.x; t < ntl; t += gridDim.x) {
;     int mt = t / d.ntiles;
;     int nt = t - mt * d.ntiles;
;     if (d.ntiles == 8) {
;       const int m4 = d.mtiles & ~3;
;       if (t < 8 * m4) {
;         const int x = t & 7, k = t >> 3;
;         nt = 4 * (x & 1) + (k & 3);
;         mt = 4 * (k >> 2) + (x >> 1);
;       }
;     }
.LBB0_446:
	s_and_b64 vcc, exec, s[0:1]
	s_cbranch_vccz .LBB0_555
	v_readlane_b32 s0, v254, 49
	s_cmp_lg_u32 s0, 1
	v_readlane_b32 s2, v255, 9
	s_cbranch_scc1 .LBB0_555
	s_mul_i32 s59, s2, s57
	v_mov_b32_e32 v0, v218
	v_readfirstlane_b32 s0, v174
	v_readfirstlane_b32 s1, v175
	s_cmp_ge_i32 s53, s59
	s_cbranch_scc1 .LBB0_555
	s_add_u32 s4, s0, 0x11d32100
	s_addc_u32 s5, s1, 0
	v_writelane_b32 v255, s4, 19
	v_and_b32_e32 v160, 31, v0
	v_bfe_u32 v3, v0, 6, 1
	v_writelane_b32 v255, s5, 20
	s_add_u32 s4, s0, 0x3280000
	s_addc_u32 s5, s1, 0
	v_writelane_b32 v255, s4, 21
	v_bfe_u32 v6, v0, 5, 1
	v_ashrrev_i32_e32 v0, 1, v0
	v_writelane_b32 v255, s5, 22
	s_add_u32 s4, s0, 0x11102100
	s_addc_u32 s5, s1, 0
	v_writelane_b32 v254, s4, 49
	v_and_b32_e32 v162, 0xffffffc0, v0
	v_lshlrev_b32_e32 v0, 4, v6
	v_writelane_b32 v254, s5, 50
	s_add_u32 s4, s0, 0x3160000
	s_addc_u32 s5, s1, 0
	v_writelane_b32 v254, s4, 46
	s_waitcnt vmcnt(0)
	v_lshl_add_u64 v[4:5], s[0:1], 0, v[0:1]
	v_lshlrev_b32_e32 v161, 6, v3
	v_writelane_b32 v254, s5, 47
	s_add_u32 s4, s0, 0x1275a100
	s_addc_u32 s5, s1, 0
	v_writelane_b32 v255, s4, 1
	v_lshlrev_b32_e32 v163, 5, v3
	v_cvt_f32_u32_e32 v3, s57
	v_writelane_b32 v255, s5, 2
	s_add_u32 s4, s0, 0x1581a100
	s_addc_u32 s5, s1, 0
	v_writelane_b32 v255, s4, 7
	v_rcp_iflag_f32_e32 v3, v3
	v_lshlrev_b32_e32 v0, 3, v6
	v_writelane_b32 v255, s5, 8
	s_add_u32 s4, s0, 0x12552100
	s_addc_u32 s5, s1, 0
	v_writelane_b32 v254, s4, 57
	v_mul_f32_e32 v3, 0x4f7ffffe, v3
	v_cvt_u32_f32_e32 v3, v3
	v_writelane_b32 v254, s5, 58
	s_add_u32 s4, s0, 0x100c2100
	s_addc_u32 s5, s1, 0
	v_writelane_b32 v254, s4, 59
	v_lshlrev_b32_e32 v2, 2, v6
	v_lshlrev_b32_e32 v140, 1, v2
	v_writelane_b32 v254, s5, 60
	s_add_u32 s4, s0, 0xe042100
	s_addc_u32 s5, s1, 0
	v_writelane_b32 v254, s4, 61
	v_lshlrev_b32_e32 v142, 1, v0
	s_mov_b32 s20, s53
	v_writelane_b32 v254, s5, 62
	s_add_u32 s4, s0, 0x9f42100
	s_addc_u32 s5, s1, 0
	v_writelane_b32 v255, s4, 5
	s_nop 1
	v_writelane_b32 v255, s5, 6
	s_add_u32 s4, s0, 0x7ec2100
	s_addc_u32 s5, s1, 0
	v_writelane_b32 v254, s4, 42
	s_nop 1
	v_writelane_b32 v254, s5, 43
	s_mov_b64 s[4:5], 0x3bb6000
	v_lshl_add_u64 v[130:131], v[4:5], 0, s[4:5]
	s_add_u32 s4, s0, 0x1789a100
	s_addc_u32 s5, s1, 0
	v_writelane_b32 v254, s4, 51
	v_lshlrev_b32_e32 v4, 6, v160
	v_mov_b32_e32 v5, v1
	v_writelane_b32 v254, s5, 52
	s_add_u32 s4, s0, 0x108e2100
	s_addc_u32 s5, s1, 0
	s_add_u32 s0, s0, 0xbfc2100
	s_addc_u32 s1, s1, 0
	v_writelane_b32 v254, s0, 55
	v_writelane_b32 v255, s4, 3
	v_lshl_add_u64 v[132:133], v[130:131], 0, v[4:5]
	v_writelane_b32 v254, s1, 56
	s_mov_b64 s[0:1], 0x4000
	v_writelane_b32 v255, s5, 4
	v_lshl_add_u64 v[134:135], v[132:133], 0, s[0:1]
	s_mov_b64 s[0:1], 0x4020
	v_lshl_add_u64 v[136:137], v[132:133], 0, s[0:1]
	v_readlane_b32 s0, v255, 12
	s_cmp_lg_u32 s0, 0
	v_readlane_b32 s0, v254, 53
	v_readlane_b32 s1, v254, 54
	s_cselect_b64 s[62:63], -1, 0
	s_nop 0
	v_lshl_add_u64 v[138:139], s[0:1], 0, v[0:1]
	s_lshl_b32 s0, s2, 3
	s_and_b32 s66, s0, 0x7fffffc0
	s_sub_i32 s0, 0, s57
	v_readfirstlane_b32 s1, v3
	s_mul_i32 s0, s0, s1
	s_mul_hi_u32 s0, s1, s0
	s_add_i32 s67, s1, s0
	s_branch .LBB0_451

; template <bool MERGE>
; DI void gemm_phase(const GemmDesc& d, const Params& P, char* lds) {
;     ...
;   for (int t = blockIdx.x; t < ntl; t += gridDim.x) {
;     int mt = t / d.ntiles;
;     int nt = t - mt * d.ntiles;
;     if (d.ntiles == 8) {
;       const int m4 = d.mtiles & ~3;
;       if (t < 8 * m4) {
;         const int x = t & 7, k = t >> 3;
;         nt = 4 * (x & 1) + (k & 3);
;         mt = 4 * (k >> 2) + (x >> 1);
;       }
;     }
.LBB0_451:
	s_abs_i32 s0, s20
	s_mul_hi_u32 s1, s0, s67
	s_mul_i32 s2, s1, s57
	s_sub_i32 s0, s0, s2
	s_add_i32 s2, s1, 1
	s_sub_i32 s4, s0, s57
	s_cmp_ge_u32 s0, s57
	s_cselect_b32 s1, s2, s1
	s_cselect_b32 s0, s4, s0
	s_add_i32 s2, s1, 1
	s_cmp_ge_u32 s0, s57
	s_cselect_b32 s0, s2, s1
	s_cmp_lt_i32 s20, s66
	v_readlane_b32 s6, v255, 10
	s_cselect_b64 s[4:5], -1, 0
	v_readlane_b32 s7, v255, 11
	s_and_b64 s[4:5], s[6:7], s[4:5]
	s_andn2_b64 vcc, exec, s[4:5]
	s_cbranch_vccnz .LBB0_453
	s_bfe_u32 s6, s20, 0x30003
	s_lshr_b32 s0, s20, 6
	s_lshl_b32 s0, s0, 3
	s_and_b32 s1, s20, 7
	s_or_b32 s2, s0, s1
	s_nop 0
	s_nop 0
	s_nop 0
	s_nop 0
	s_cmp_lt_i32 s56, 3
	s_mov_b64 s[4:5], -1
	s_cbranch_scc1 .LBB0_457
	s_branch .LBB0_454
